# attnA: s_setprio 1 around the QK + first P.V MFMA section of each step (as hipcc does around its GEMM MFMA clusters)
# baseline (speedup 1.0000x reference)
; #define MFMA32(a, b, c) __builtin_amdgcn_mfma_f32_32x32x16_bf16((a), (b), (c), 0, 0, 0)
; __device__ __forceinline__ bf16x8 v_build(const VRaw& r, int ks) { return (bf16x8){r.lo[ks][0], r.lo[ks][1], r.lo[ks][2], r.lo[ks][3], r.hv[ks][0], r.hv[ks][1], r.hv[ks][2], r.hv[ks][3]}; }
; #define SB_ __builtin_amdgcn_sched_barrier(0)
; #define EX4_(S, B) do { S[B] = fexp2(S[B]); S[B + 1] = fexp2(S[B + 1]); S[B + 2] = fexp2(S[B + 2]); S[B + 3] = fexp2(S[B + 3]); } while (0)
; __device__ __forceinline__ void attnA_unit(const P2Ctx& C, int b, int h, int qb) {
;     ...
;             __builtin_amdgcn_s_setprio(1);
; #pragma unroll
;             for (int ks = 0; ks < 4; ++ks) o[0] = MFMA32(v_build(va, ks), pf_[ks], o[0]);
;             EX4_(s[0], 0); EX4_(s[0], 4); EX4_(s[0], 8); EX4_(s[0], 12);
;             SB_; v_issue<4>(vimg, 1, lane, va); v_wait(va);
; #pragma unroll
;             for (int ks = 0; ks < 4; ++ks) o[1] = MFMA32(v_build(va, ks), pf_[ks], o[1]);
;             EX4_(s[1], 0); EX4_(s[1], 4); EX4_(s[1], 8); EX4_(s[1], 12);
.LaA_nodma_7:
	s_setprio 1
	s_waitcnt lgkmcnt(7)
	v_mfma_f32_32x32x16_bf16 v[68:83], v[100:103], v[164:167], v[220:235]
	ds_read_b64_tr_b16 v[132:133], v237 offset:0
	ds_read_b64_tr_b16 v[134:135], v237 offset:2048
	s_waitcnt lgkmcnt(8)
	v_mfma_f32_32x32x16_bf16 v[84:99], v[104:107], v[164:167], v[220:235]
	ds_read_b64_tr_b16 v[136:137], v237 offset:4096
	ds_read_b64_tr_b16 v[138:139], v237 offset:6144
	s_waitcnt lgkmcnt(9)
	v_mfma_f32_32x32x16_bf16 v[68:83], v[108:111], v[168:171], v[68:83]
	ds_read_b64_tr_b16 v[140:141], v237 offset:8192
	ds_read_b64_tr_b16 v[142:143], v237 offset:10240
	s_waitcnt lgkmcnt(10)
	v_mfma_f32_32x32x16_bf16 v[84:99], v[112:115], v[168:171], v[84:99]
	ds_read_b64_tr_b16 v[144:145], v237 offset:12288
	ds_read_b64_tr_b16 v[146:147], v237 offset:14336
	s_waitcnt lgkmcnt(11)
	v_mfma_f32_32x32x16_bf16 v[68:83], v[116:119], v[172:175], v[68:83]
	s_waitcnt lgkmcnt(10)
	v_mfma_f32_32x32x16_bf16 v[84:99], v[120:123], v[172:175], v[84:99]
	s_waitcnt lgkmcnt(9)
	v_mfma_f32_32x32x16_bf16 v[68:83], v[124:127], v[176:179], v[68:83]
	s_waitcnt lgkmcnt(8)
	v_mfma_f32_32x32x16_bf16 v[84:99], v[128:131], v[176:179], v[84:99]
	s_waitcnt lgkmcnt(0)
	ds_read_b64_tr_b16 v[148:149], v237 offset:512
	ds_read_b64_tr_b16 v[150:151], v237 offset:2560
	v_mfma_f32_32x32x16_bf16 v[4:19], v[132:135], v[180:183], v[4:19]
	ds_read_b64_tr_b16 v[152:153], v237 offset:4608
	ds_read_b64_tr_b16 v[154:155], v237 offset:6656
	ds_read_b64_tr_b16 v[156:157], v237 offset:8704
	v_mfma_f32_32x32x16_bf16 v[4:19], v[136:139], v[184:187], v[4:19]
	ds_read_b64_tr_b16 v[158:159], v237 offset:10752
	ds_read_b64_tr_b16 v[160:161], v237 offset:12800
	ds_read_b64_tr_b16 v[162:163], v237 offset:14848
	v_mfma_f32_32x32x16_bf16 v[4:19], v[140:143], v[188:191], v[4:19]
	v_mfma_f32_32x32x16_bf16 v[4:19], v[144:147], v[192:195], v[4:19]
	s_lshl_b32 s6, s14, 6
	s_cmp_gt_i32 s6, s26
	s_cbranch_scc1 .LaA_near_8
.LaA_far_9:
	s_waitcnt lgkmcnt(0)
	ds_read_b64_tr_b16 v[132:133], v237 offset:1024
	ds_read_b64_tr_b16 v[134:135], v237 offset:3072
	v_mfma_f32_32x32x16_bf16 v[20:35], v[148:151], v[180:183], v[20:35]
	ds_read_b64_tr_b16 v[136:137], v237 offset:5120
	ds_read_b64_tr_b16 v[138:139], v237 offset:7168
	ds_read_b64_tr_b16 v[140:141], v237 offset:9216
	v_max_f32_e32 v242, v68, v69
	v_max_f32_e32 v243, v84, v85
	v_max3_f32 v242, v242, v70, v71
	v_max3_f32 v243, v243, v86, v87
	v_max3_f32 v242, v242, v72, v73
	v_mfma_f32_32x32x16_bf16 v[20:35], v[152:155], v[184:187], v[20:35]
	ds_read_b64_tr_b16 v[142:143], v237 offset:11264
	ds_read_b64_tr_b16 v[144:145], v237 offset:13312
	ds_read_b64_tr_b16 v[146:147], v237 offset:15360
	v_max3_f32 v243, v243, v88, v89
	v_max3_f32 v242, v242, v74, v75
	v_max3_f32 v243, v243, v90, v91
	v_max3_f32 v242, v242, v76, v77
	v_max3_f32 v243, v243, v92, v93
	v_mfma_f32_32x32x16_bf16 v[20:35], v[156:159], v[188:191], v[20:35]
	v_max3_f32 v242, v242, v78, v79
	v_max3_f32 v243, v243, v94, v95
	v_max3_f32 v242, v242, v80, v81
	v_max3_f32 v243, v243, v96, v97
	v_max3_f32 v242, v242, v82, v83
	v_mfma_f32_32x32x16_bf16 v[20:35], v[160:163], v[192:195], v[20:35]
	v_max3_f32 v243, v243, v98, v99
	v_max_f32_e32 v242, v242, v243
	s_setprio 0
	v_mov_b32_e32 v243, v242
	s_nop 1
	v_permlane32_swap_b32 v243, v242
	v_max_f32_e32 v247, v243, v242
	v_cmp_lt_f32_e32 vcc, 0x41000000, v247
	s_cmp_lg_u64 vcc, 0
	s_cbranch_scc1 .LaA_resc_pre

; #define LAS __attribute__((address_space(3)))
; __device__ __forceinline__ void attnA_unit(const P2Ctx& C, int b, int h, int qb) {
;     ...
;     if (NT - 1 < ntw && !(pf & 2)) A_PV(NT - 1);
;     __syncthreads();
;     ...
;     l += __shfl_xor(l, 32);
;     const float inv = 1.0f / l;
;     LAS float* X2 = (LAS float*)(lds + 65536);
;     if (comp == 1) {
; #pragma unroll
;         for (int cb = 0; cb < 4; ++cb)
; #pragma unroll
;             for (int r = 0; r < 16; ++r) X2[((qs * 4 + cb) * 16 + r) * 64 + lane] = o[cb][r] * inv;
;     }
.LaA_loopexit:
	s_setprio 0
	s_cmp_eq_u32 s13, s12
	s_cbranch_scc0 .LaA_nofinalpv_14
	s_add_i32 s7, s14, -1
	s_and_b32 s7, s7, 3
	s_lshl_b32 s7, s7, 15
	v_add_u32_e32 v237, s7, v204
	ds_read_b64_tr_b16 v[132:133], v237 offset:0
	ds_read_b64_tr_b16 v[134:135], v237 offset:2048
	ds_read_b64_tr_b16 v[136:137], v237 offset:4096
	ds_read_b64_tr_b16 v[138:139], v237 offset:6144
	ds_read_b64_tr_b16 v[140:141], v237 offset:8192
	ds_read_b64_tr_b16 v[142:143], v237 offset:10240
	ds_read_b64_tr_b16 v[144:145], v237 offset:12288
	ds_read_b64_tr_b16 v[146:147], v237 offset:14336
	s_waitcnt lgkmcnt(0)
	ds_read_b64_tr_b16 v[148:149], v237 offset:512
	ds_read_b64_tr_b16 v[150:151], v237 offset:2560
	v_mfma_f32_32x32x16_bf16 v[4:19], v[132:135], v[180:183], v[4:19]
	ds_read_b64_tr_b16 v[152:153], v237 offset:4608
	ds_read_b64_tr_b16 v[154:155], v237 offset:6656
	ds_read_b64_tr_b16 v[156:157], v237 offset:8704
	v_mfma_f32_32x32x16_bf16 v[4:19], v[136:139], v[184:187], v[4:19]
	ds_read_b64_tr_b16 v[158:159], v237 offset:10752
	ds_read_b64_tr_b16 v[160:161], v237 offset:12800
	ds_read_b64_tr_b16 v[162:163], v237 offset:14848
	v_mfma_f32_32x32x16_bf16 v[4:19], v[140:143], v[188:191], v[4:19]
	v_mfma_f32_32x32x16_bf16 v[4:19], v[144:147], v[192:195], v[4:19]
	s_waitcnt lgkmcnt(0)
	ds_read_b64_tr_b16 v[132:133], v237 offset:1024
	ds_read_b64_tr_b16 v[134:135], v237 offset:3072
	v_mfma_f32_32x32x16_bf16 v[20:35], v[148:151], v[180:183], v[20:35]
	ds_read_b64_tr_b16 v[136:137], v237 offset:5120
	ds_read_b64_tr_b16 v[138:139], v237 offset:7168
	ds_read_b64_tr_b16 v[140:141], v237 offset:9216
	v_mfma_f32_32x32x16_bf16 v[20:35], v[152:155], v[184:187], v[20:35]
	ds_read_b64_tr_b16 v[142:143], v237 offset:11264
	ds_read_b64_tr_b16 v[144:145], v237 offset:13312
	ds_read_b64_tr_b16 v[146:147], v237 offset:15360
	v_mfma_f32_32x32x16_bf16 v[20:35], v[156:159], v[188:191], v[20:35]
	v_mfma_f32_32x32x16_bf16 v[20:35], v[160:163], v[192:195], v[20:35]
	s_waitcnt lgkmcnt(0)
	ds_read_b64_tr_b16 v[148:149], v237 offset:1536
	ds_read_b64_tr_b16 v[150:151], v237 offset:3584
	v_mfma_f32_32x32x16_bf16 v[36:51], v[132:135], v[180:183], v[36:51]
	ds_read_b64_tr_b16 v[152:153], v237 offset:5632
	ds_read_b64_tr_b16 v[154:155], v237 offset:7680
	ds_read_b64_tr_b16 v[156:157], v237 offset:9728
	v_mfma_f32_32x32x16_bf16 v[36:51], v[136:139], v[184:187], v[36:51]
	ds_read_b64_tr_b16 v[158:159], v237 offset:11776
	ds_read_b64_tr_b16 v[160:161], v237 offset:13824
	ds_read_b64_tr_b16 v[162:163], v237 offset:15872
	v_mfma_f32_32x32x16_bf16 v[36:51], v[140:143], v[188:191], v[36:51]
	v_mfma_f32_32x32x16_bf16 v[36:51], v[144:147], v[192:195], v[36:51]
	s_waitcnt lgkmcnt(0)
	v_mfma_f32_32x32x16_bf16 v[52:67], v[148:151], v[180:183], v[52:67]
	v_mfma_f32_32x32x16_bf16 v[52:67], v[152:155], v[184:187], v[52:67]
	v_mfma_f32_32x32x16_bf16 v[52:67], v[156:159], v[188:191], v[52:67]
	v_mfma_f32_32x32x16_bf16 v[52:67], v[160:163], v[192:195], v[52:67]
.LaA_nofinalpv_14:
	s_waitcnt lgkmcnt(0)
	s_barrier
	v_mov_b32_e32 v243, v241
	s_nop 1
	v_permlane32_swap_b32 v243, v241
	v_add_f32_e32 v241, v243, v241
	v_rcp_f32_e32 v241, v241
	s_lshl_b32 s6, s9, 14
	s_add_i32 s6, s6, 0x10000
	v_lshlrev_b32_e32 v2, 2, v219
	v_add_u32_e32 v2, s6, v2
	s_cmp_eq_u32 s8, 0
	s_cbranch_scc1 .LaA_comp0_15
	s_nop 7
	s_nop 3
	v_mul_f32_e32 v68, v4, v241
	ds_write_b32 v2, v68 offset:0
	v_mul_f32_e32 v69, v5, v241
	ds_write_b32 v2, v69 offset:256
	v_mul_f32_e32 v68, v6, v241
	ds_write_b32 v2, v68 offset:512
	v_mul_f32_e32 v69, v7, v241
	ds_write_b32 v2, v69 offset:768
	v_mul_f32_e32 v68, v8, v241
	ds_write_b32 v2, v68 offset:1024
	v_mul_f32_e32 v69, v9, v241
	ds_write_b32 v2, v69 offset:1280
	v_mul_f32_e32 v68, v10, v241
	ds_write_b32 v2, v68 offset:1536
	v_mul_f32_e32 v69, v11, v241
	ds_write_b32 v2, v69 offset:1792
	v_mul_f32_e32 v68, v12, v241
	ds_write_b32 v2, v68 offset:2048
	v_mul_f32_e32 v69, v13, v241
	ds_write_b32 v2, v69 offset:2304
	v_mul_f32_e32 v68, v14, v241
	ds_write_b32 v2, v68 offset:2560
	v_mul_f32_e32 v69, v15, v241
	ds_write_b32 v2, v69 offset:2816
	v_mul_f32_e32 v68, v16, v241
	ds_write_b32 v2, v68 offset:3072
	v_mul_f32_e32 v69, v17, v241
	ds_write_b32 v2, v69 offset:3328
	v_mul_f32_e32 v68, v18, v241
	ds_write_b32 v2, v68 offset:3584
	v_mul_f32_e32 v69, v19, v241
	ds_write_b32 v2, v69 offset:3840
	v_mul_f32_e32 v68, v20, v241
	ds_write_b32 v2, v68 offset:4096
	v_mul_f32_e32 v69, v21, v241
	ds_write_b32 v2, v69 offset:4352
	v_mul_f32_e32 v68, v22, v241
	ds_write_b32 v2, v68 offset:4608
	v_mul_f32_e32 v69, v23, v241
	ds_write_b32 v2, v69 offset:4864
	v_mul_f32_e32 v68, v24, v241
	ds_write_b32 v2, v68 offset:5120
	v_mul_f32_e32 v69, v25, v241
	ds_write_b32 v2, v69 offset:5376
	v_mul_f32_e32 v68, v26, v241
	ds_write_b32 v2, v68 offset:5632
	v_mul_f32_e32 v69, v27, v241
	ds_write_b32 v2, v69 offset:5888
	v_mul_f32_e32 v68, v28, v241
	ds_write_b32 v2, v68 offset:6144
	v_mul_f32_e32 v69, v29, v241
	ds_write_b32 v2, v69 offset:6400
	v_mul_f32_e32 v68, v30, v241
	ds_write_b32 v2, v68 offset:6656
	v_mul_f32_e32 v69, v31, v241
	ds_write_b32 v2, v69 offset:6912
	v_mul_f32_e32 v68, v32, v241
	ds_write_b32 v2, v68 offset:7168
	v_mul_f32_e32 v69, v33, v241
	ds_write_b32 v2, v69 offset:7424
	v_mul_f32_e32 v68, v34, v241
	ds_write_b32 v2, v68 offset:7680
	v_mul_f32_e32 v69, v35, v241
	ds_write_b32 v2, v69 offset:7936
	v_mul_f32_e32 v68, v36, v241
	ds_write_b32 v2, v68 offset:8192
	v_mul_f32_e32 v69, v37, v241
	ds_write_b32 v2, v69 offset:8448
	v_mul_f32_e32 v68, v38, v241
	ds_write_b32 v2, v68 offset:8704
	v_mul_f32_e32 v69, v39, v241
	ds_write_b32 v2, v69 offset:8960
	v_mul_f32_e32 v68, v40, v241
	ds_write_b32 v2, v68 offset:9216
; __device__ __forceinline__ void attnA_unit(const P2Ctx& C, int b, int h, int qb) {
;     ...
;     if (comp == 1) {
; #pragma unroll
;         for (int cb = 0; cb < 4; ++cb)
; #pragma unroll
;             for (int r = 0; r < 16; ++r) X2[((qs * 4 + cb) * 16 + r) * 64 + lane] = o[cb][r] * inv;
;     }
;     __syncthreads();
	v_mul_f32_e32 v69, v41, v241
	ds_write_b32 v2, v69 offset:9472
	v_mul_f32_e32 v68, v42, v241
	ds_write_b32 v2, v68 offset:9728
	v_mul_f32_e32 v69, v43, v241
	ds_write_b32 v2, v69 offset:9984
	v_mul_f32_e32 v68, v44, v241
	ds_write_b32 v2, v68 offset:10240
	v_mul_f32_e32 v69, v45, v241
	ds_write_b32 v2, v69 offset:10496
	v_mul_f32_e32 v68, v46, v241
	ds_write_b32 v2, v68 offset:10752
	v_mul_f32_e32 v69, v47, v241
	ds_write_b32 v2, v69 offset:11008
	v_mul_f32_e32 v68, v48, v241
	ds_write_b32 v2, v68 offset:11264
	v_mul_f32_e32 v69, v49, v241
	ds_write_b32 v2, v69 offset:11520
	v_mul_f32_e32 v68, v50, v241
	ds_write_b32 v2, v68 offset:11776
	v_mul_f32_e32 v69, v51, v241
	ds_write_b32 v2, v69 offset:12032
	v_mul_f32_e32 v68, v52, v241
	ds_write_b32 v2, v68 offset:12288
	v_mul_f32_e32 v69, v53, v241
	ds_write_b32 v2, v69 offset:12544
	v_mul_f32_e32 v68, v54, v241
	ds_write_b32 v2, v68 offset:12800
	v_mul_f32_e32 v69, v55, v241
	ds_write_b32 v2, v69 offset:13056
	v_mul_f32_e32 v68, v56, v241
	ds_write_b32 v2, v68 offset:13312
	v_mul_f32_e32 v69, v57, v241
	ds_write_b32 v2, v69 offset:13568
	v_mul_f32_e32 v68, v58, v241
	ds_write_b32 v2, v68 offset:13824
	v_mul_f32_e32 v69, v59, v241
	ds_write_b32 v2, v69 offset:14080
	v_mul_f32_e32 v68, v60, v241
	ds_write_b32 v2, v68 offset:14336
	v_mul_f32_e32 v69, v61, v241
	ds_write_b32 v2, v69 offset:14592
	v_mul_f32_e32 v68, v62, v241
	ds_write_b32 v2, v68 offset:14848
	v_mul_f32_e32 v69, v63, v241
	ds_write_b32 v2, v69 offset:15104
	v_mul_f32_e32 v68, v64, v241
	ds_write_b32 v2, v68 offset:15360
	v_mul_f32_e32 v69, v65, v241
	ds_write_b32 v2, v69 offset:15616
	v_mul_f32_e32 v68, v66, v241
	ds_write_b32 v2, v68 offset:15872
	v_mul_f32_e32 v69, v67, v241
	ds_write_b32 v2, v69 offset:16128
	s_waitcnt lgkmcnt(0)
	s_barrier
	s_branch .LaA_epiend_16
	s_nop 0
	s_nop 0
	s_nop 0
	s_nop 0
	s_nop 0
	s_nop 0
	s_nop 0
	s_nop 0
	s_nop 0
	s_nop 0
	s_nop 0
	s_nop 0
	s_nop 0
	s_nop 0
	s_nop 0
	s_nop 0
	s_nop 0
	s_nop 0
	s_nop 0
	s_nop 0
	s_nop 0
	s_nop 0
	s_nop 0
	s_nop 0
	s_nop 0
	s_nop 0
	s_nop 0
	s_nop 0
	s_nop 0
	s_nop 0
	s_nop 0
	s_nop 0
	s_nop 0
	s_nop 0
	s_nop 0
	s_nop 0
	s_nop 0
	s_nop 0
	s_nop 0
	s_nop 0
	s_nop 0
	s_nop 0
	s_nop 0
	s_nop 0
	s_nop 0
	s_nop 0
	s_nop 0
	s_nop 0
	s_nop 0
	s_nop 0
	s_nop 0
	s_nop 0
	s_nop 0
	s_nop 0
	s_nop 0
	s_nop 0
	s_nop 0
	s_nop 0
	s_nop 0
	s_nop 0
	s_nop 0
	s_nop 0
	s_nop 0
	s_nop 0
	s_nop 0
	s_nop 0
	s_nop 0
	s_nop 0
	s_nop 0
	s_nop 0
	s_nop 0
	s_nop 0
	s_nop 0
	s_nop 0
	s_nop 0
	s_nop 0
	s_nop 0
	s_nop 0
	s_nop 0
	s_nop 0
	s_nop 0
	s_nop 0
	s_nop 0
	s_nop 0
	s_nop 0
	s_nop 0
	s_nop 0
	s_nop 0
	s_nop 0
	s_nop 0
	s_nop 0
	s_nop 0
	s_nop 0
	s_nop 0
	s_nop 0
	s_nop 0
	s_nop 0
	s_nop 0
	s_nop 0
	s_nop 0
	s_nop 0
	s_nop 0
	s_nop 0
	s_nop 0
	s_nop 0
	s_nop 0
	s_nop 0
	s_nop 0
	s_nop 0
	s_nop 0
	s_nop 0
	s_nop 0
	s_nop 0
	s_nop 0
	s_nop 0
	s_nop 0
	s_nop 0
	s_nop 0
	s_nop 0
	s_nop 0
	s_nop 0
	s_nop 0
	s_nop 0
	s_nop 0
	s_nop 0
	s_nop 0
	s_nop 0
	s_nop 0
	s_nop 0
	s_nop 0
	s_nop 0
	s_nop 0
	s_nop 0
	s_nop 0
	s_nop 0
	s_nop 0
	s_nop 0
	s_nop 0
	s_nop 0
	s_nop 0
	s_nop 0
	s_nop 0
	s_nop 0
	s_nop 0
	s_nop 0
	s_nop 0
	s_nop 0
	s_nop 0
	s_nop 0
	s_nop 0
	s_nop 0
	s_nop 0
	s_nop 0
	s_nop 0
	s_nop 0
	s_nop 0
	s_nop 0
	s_nop 0
	s_nop 0
	s_nop 0
	s_nop 0
	s_nop 0
	s_nop 0
	s_nop 0
	s_nop 0
	s_nop 0
	s_nop 0
	s_nop 0
	s_nop 0
	s_nop 0
	s_nop 0
	s_nop 0
	s_nop 0
	s_nop 0
	s_nop 0
	s_nop 0
	s_nop 0
	s_nop 0
	s_nop 0
	s_nop 0
	s_nop 0
	s_nop 0
	s_nop 0
	s_nop 0
	s_nop 0
	s_nop 0
	s_nop 0
	s_nop 0
	s_nop 0
	s_nop 0
	s_nop 0
	s_nop 0
	s_nop 0
	s_nop 0
	s_nop 0
	s_nop 0
	s_nop 0
	s_nop 0
	s_nop 0
	s_nop 0
	s_nop 0
	s_nop 0
	s_nop 0
	s_nop 0
	s_nop 0
	s_nop 0
	s_nop 0
	s_nop 0
	s_nop 0
	s_nop 0
	s_nop 0
	s_nop 0
	s_nop 0
	s_nop 0
	s_nop 0
	s_nop 0
	s_nop 0
	s_nop 0
	s_nop 0
	s_nop 0
	s_nop 0
	s_nop 0
	s_nop 0
	s_nop 0
	s_nop 0
	s_nop 0
	s_nop 0
	s_nop 0
	s_nop 0
	s_nop 0
	s_nop 0
	s_nop 0
	s_nop 0
	s_nop 0
	s_nop 0
	s_nop 0
	s_nop 0
	s_nop 0
	s_nop 0
	s_nop 0
	s_nop 0
	s_nop 0
	s_nop 0
	s_nop 0
	s_nop 0
	s_nop 0
	s_nop 0
	s_nop 0
	s_nop 0
	s_nop 0
	s_nop 0
	s_nop 0
	s_nop 0
	s_nop 0
	s_nop 0
	s_nop 0
	s_nop 0
	s_nop 0
	s_nop 0
	s_nop 0
	s_nop 0
	s_nop 0
	s_nop 0
	s_nop 0
	s_nop 0
	s_nop 0
	s_nop 0
	s_nop 0
	s_nop 0
	s_nop 0
	s_nop 0
	s_nop 0
	s_nop 0
	s_nop 0
	s_nop 0
	s_nop 0
	s_nop 0
	s_nop 0
	s_nop 0
	s_nop 0
	s_nop 0
	s_nop 0
	s_nop 0
	s_nop 0
	s_nop 0
	s_nop 0
	s_nop 0
	s_nop 0
	s_nop 0
	s_nop 0
	s_nop 0
	s_nop 0
	s_nop 0
	s_nop 0
	s_nop 0
	s_nop 0
	s_nop 0
	s_nop 0
	s_nop 0
	s_nop 0
	s_nop 0
	s_nop 0
	s_nop 0
	s_nop 0
	s_nop 0
	s_nop 0
	s_nop 0
	s_nop 0
	s_nop 0
	s_nop 0
	s_nop 0
	s_nop 0
	s_nop 0
	s_nop 0
	s_nop 0
	s_nop 0
	s_nop 0
	s_nop 0
	s_nop 0
	s_nop 0
	s_nop 0
	s_nop 0
	s_nop 0
	s_nop 0
	s_nop 0
	s_nop 0
	s_nop 0
	s_nop 0
	s_nop 0
	s_nop 0
	s_nop 0
	s_nop 0
	s_nop 0
	s_nop 0
	s_nop 0
	s_nop 0
	s_nop 0
	s_nop 0
	s_nop 0
	s_nop 0
	s_nop 0
	s_nop 0
	s_nop 0
	s_nop 0
	s_nop 0
	s_nop 0
	s_nop 0
	s_nop 0
	s_nop 0
	s_nop 0
	s_nop 0
	s_nop 0
	s_nop 0
	s_nop 0
	s_nop 0
	s_nop 0
	s_nop 0
	s_nop 0
	s_nop 0
	s_nop 0
	s_nop 0
	s_nop 0
	s_nop 0
	s_nop 0
	s_nop 0
	s_nop 0
	s_nop 0
	s_nop 0
	s_nop 0
	s_nop 0
	s_nop 0
	s_nop 0
	s_nop 0
	s_nop 0
	s_nop 0
	s_nop 0
	s_nop 0
	s_nop 0
	s_nop 0
	s_nop 0
	s_nop 0
	s_nop 0
	s_nop 0
	s_nop 0
	s_nop 0
	s_nop 0
	s_nop 0
	s_nop 0
	s_nop 0
	s_nop 0
	s_nop 0
	s_nop 0
	s_nop 0
	s_nop 0
	s_nop 0
	s_nop 0
	s_nop 0
	s_nop 0
	s_nop 0
	s_nop 0
	s_nop 0
	s_nop 0
	s_nop 0
	s_nop 0
	s_nop 0
	s_nop 0
	s_nop 0
	s_nop 0
	s_nop 0
	s_nop 0
	s_nop 0
	s_nop 0
	s_nop 0
	s_nop 0
	s_nop 0
	s_nop 0
	s_nop 0
	s_nop 0
	s_nop 0
	s_nop 0
	s_nop 0
	s_nop 0
	s_nop 0
	s_nop 0
	s_nop 0
	s_nop 0
; __device__ __forceinline__ void subln_store(f32x16 (&o)[4], const float* subg, bf16_t* dst  , int lane) {
;     ...
;     f32x4 sg[4][4];
; #pragma unroll
;     for (int cb = 0; cb < 4; ++cb)
; #pragma unroll
;         for (int g = 0; g < 4; ++g) sg[cb][g] = *(const f32x4*)(subg + 32 * cb + 8 * g + 4 * hi);
; __device__ __forceinline__ void attnA_unit(const P2Ctx& C, int b, int h, int qb) {
;     ...
;     if (comp == 0) {
; #pragma unroll
;         for (int cb = 0; cb < 4; ++cb)
; #pragma unroll
;             for (int r = 0; r < 16; ++r) o[cb][r] = o[cb][r] * inv - lam * X2[((qs * 4 + cb) * 16 + r) * 64 + lane];
	s_nop 0
	s_nop 0
	s_nop 0
	s_nop 0
	s_nop 0
	s_nop 0
	s_nop 0
	s_nop 0
	s_nop 0
	s_nop 0
	s_nop 0
	s_nop 0
	s_nop 0
	s_nop 0
	s_nop 0
	s_nop 0
	s_nop 0
	s_nop 0
	s_nop 0
	s_nop 0
	s_nop 0
	s_nop 0
	s_nop 0
	s_nop 0
	s_nop 0
	s_nop 0
	s_nop 0
	s_nop 0
	s_nop 0
	s_nop 0
	s_nop 0
	s_nop 0
	s_nop 0
	s_nop 0
	s_nop 0
	s_nop 0
	s_nop 0
	s_nop 0
	s_nop 0
	s_nop 0
	s_nop 0
	s_nop 0
	s_nop 0
	s_nop 0
	s_nop 0
	s_nop 0
	s_nop 0
	s_nop 0
	s_nop 0
	s_nop 0
	s_nop 0
	s_nop 0
	s_nop 0
	s_nop 0
	s_nop 0
	s_nop 0
	s_nop 0
	s_nop 0
	s_nop 0
	s_nop 0
	s_nop 0
	s_nop 0
	s_nop 0
	s_nop 0
	s_nop 0
	s_nop 0
	s_nop 0
	s_nop 0
	s_nop 0
	s_nop 0
	s_nop 0
	s_nop 0
	s_nop 0
	s_nop 0
	s_nop 0
	s_nop 0
	s_nop 0
	s_nop 0
	s_nop 0
	s_nop 0
	s_nop 0
	s_nop 0
	s_nop 0
	s_nop 0
	s_nop 0
	s_nop 0
	s_nop 0
	s_nop 0
	s_nop 0
	s_nop 0
	s_nop 0
	s_nop 0
	s_nop 0
	s_nop 0
	s_nop 0
	s_nop 0
	s_nop 0
	s_nop 0
	s_nop 0
	s_nop 0
	s_nop 0
	s_nop 0
	s_nop 0
	s_nop 0
	s_nop 0
	s_nop 0
	s_nop 0
	s_nop 0
	s_nop 0
	s_nop 0
	s_nop 0
	s_nop 0
	s_nop 0
	s_nop 0
	s_nop 0
	s_nop 0
	s_nop 0
	s_nop 0
	s_nop 0
	s_nop 0
	s_nop 0
	s_nop 0
	s_nop 0
	s_nop 0
	s_nop 0
	s_nop 0
	s_nop 0
	s_nop 0
	s_nop 0
	s_nop 0
	s_nop 0
	s_nop 0
	s_nop 0
	s_nop 0
	s_nop 0
	s_nop 0
	s_nop 0
	s_nop 0
	s_nop 0
	s_nop 0
	s_nop 0
	s_nop 0
	s_nop 0
	s_nop 0
	s_nop 0
	s_nop 0
	s_nop 0
	s_nop 0
	s_nop 0
	s_nop 0
	s_nop 0
	s_nop 0
	s_nop 0
	s_nop 0
	s_nop 0
	s_nop 0
	s_nop 0
	s_nop 0
	s_nop 0
	s_nop 0
	s_nop 0
	s_nop 0
	s_nop 0
	s_nop 0
	s_nop 0
	s_nop 0
	s_nop 0
	s_nop 0
	s_nop 0
	s_nop 0
	s_nop 0
	s_nop 0
	s_nop 0
	s_nop 0
	s_nop 0
	s_nop 0
	s_nop 0
	s_nop 0
	s_nop 0
	s_nop 0
	s_nop 0
	s_nop 0
	s_nop 0
	s_nop 0
	s_nop 0
	s_nop 0
	s_nop 0
	s_nop 0
	s_nop 0
	s_nop 0
	s_nop 0
	s_nop 0
	s_nop 0
	s_nop 0
	s_nop 0
	s_nop 0
	s_nop 0
	s_nop 0
	s_nop 0
	s_nop 0
	s_nop 0
	s_nop 0
	s_nop 0
	s_nop 0
	s_nop 0
	s_nop 0
	s_nop 0
	s_nop 0
	s_nop 0
	s_nop 0
	s_nop 0
	s_nop 0
	s_nop 0
	s_nop 0
	s_nop 0
	s_nop 0
	s_nop 0
	s_nop 0
	s_nop 0
	s_nop 0
	s_nop 0
	s_nop 0
	s_nop 0
	s_nop 0
	s_nop 0
	s_nop 0
	s_nop 0
	s_nop 0
	s_nop 0
	s_nop 0
	s_nop 0
	s_nop 0
	s_nop 0
	s_nop 0
	s_nop 0
	s_nop 0
	s_nop 0
	s_nop 0
	s_nop 0
	s_nop 0
	s_nop 0
	s_nop 0
	s_nop 0
	s_nop 0
	s_nop 0
	s_nop 0
	s_nop 0
	s_nop 0
	s_nop 0
	s_nop 0
	s_nop 0
	s_nop 0
	s_nop 0
.LaA_comp0_15:
	v_lshrrev_b32_e32 v242, 5, v219
	v_lshlrev_b32_e32 v242, 4, v242
	v_add_u32_e32 v242, 0x22a00, v242
	ds_read_b128 v[100:103], v242 offset:0
	ds_read_b128 v[104:107], v242 offset:32
	ds_read_b128 v[108:111], v242 offset:64
	ds_read_b128 v[112:115], v242 offset:96
	ds_read_b128 v[116:119], v242 offset:128
	ds_read_b128 v[120:123], v242 offset:160
	ds_read_b128 v[124:127], v242 offset:192
	ds_read_b128 v[128:131], v242 offset:224
	s_waitcnt lgkmcnt(4)
	ds_read_b128 v[132:135], v242 offset:256
	ds_read_b128 v[136:139], v242 offset:288
	ds_read_b128 v[140:143], v242 offset:320
	ds_read_b128 v[144:147], v242 offset:352
	ds_read_b128 v[148:151], v242 offset:384
	ds_read_b128 v[152:155], v242 offset:416
	ds_read_b128 v[156:159], v242 offset:448
	ds_read_b128 v[160:163], v242 offset:480
	s_waitcnt lgkmcnt(6)
	ds_read_b32 v243, v207
	s_nop 7
	s_nop 3
	v_mul_f32_e32 v4, v4, v241
	v_mul_f32_e32 v5, v5, v241
	v_mul_f32_e32 v6, v6, v241
	v_mul_f32_e32 v7, v7, v241
	v_mul_f32_e32 v8, v8, v241
	v_mul_f32_e32 v9, v9, v241
	v_mul_f32_e32 v10, v10, v241
	v_mul_f32_e32 v11, v11, v241
	v_mul_f32_e32 v12, v12, v241
	v_mul_f32_e32 v13, v13, v241
	v_mul_f32_e32 v14, v14, v241
	v_mul_f32_e32 v15, v15, v241
	v_mul_f32_e32 v16, v16, v241
	v_mul_f32_e32 v17, v17, v241
	v_mul_f32_e32 v18, v18, v241
	v_mul_f32_e32 v19, v19, v241
	v_mul_f32_e32 v20, v20, v241
	v_mul_f32_e32 v21, v21, v241
	v_mul_f32_e32 v22, v22, v241
	v_mul_f32_e32 v23, v23, v241
	v_mul_f32_e32 v24, v24, v241
	v_mul_f32_e32 v25, v25, v241
	v_mul_f32_e32 v26, v26, v241
	v_mul_f32_e32 v27, v27, v241
	v_mul_f32_e32 v28, v28, v241
	v_mul_f32_e32 v29, v29, v241
	v_mul_f32_e32 v30, v30, v241
	v_mul_f32_e32 v31, v31, v241
	v_mul_f32_e32 v32, v32, v241
	v_mul_f32_e32 v33, v33, v241
	v_mul_f32_e32 v34, v34, v241
	v_mul_f32_e32 v35, v35, v241
	v_mul_f32_e32 v36, v36, v241
	v_mul_f32_e32 v37, v37, v241
	v_mul_f32_e32 v38, v38, v241
	v_mul_f32_e32 v39, v39, v241
	v_mul_f32_e32 v40, v40, v241
	v_mul_f32_e32 v41, v41, v241
	v_mul_f32_e32 v42, v42, v241
	v_mul_f32_e32 v43, v43, v241
	v_mul_f32_e32 v44, v44, v241
	v_mul_f32_e32 v45, v45, v241
	v_mul_f32_e32 v46, v46, v241
	v_mul_f32_e32 v47, v47, v241
	v_mul_f32_e32 v48, v48, v241
	v_mul_f32_e32 v49, v49, v241
	v_mul_f32_e32 v50, v50, v241
	v_mul_f32_e32 v51, v51, v241
	v_mul_f32_e32 v52, v52, v241
	v_mul_f32_e32 v53, v53, v241
	v_mul_f32_e32 v54, v54, v241
	v_mul_f32_e32 v55, v55, v241
	v_mul_f32_e32 v56, v56, v241
	v_mul_f32_e32 v57, v57, v241
	v_mul_f32_e32 v58, v58, v241
	v_mul_f32_e32 v59, v59, v241
	v_mul_f32_e32 v60, v60, v241
	v_mul_f32_e32 v61, v61, v241
	v_mul_f32_e32 v62, v62, v241
	v_mul_f32_e32 v63, v63, v241
	v_mul_f32_e32 v64, v64, v241
	v_mul_f32_e32 v65, v65, v241
	v_mul_f32_e32 v66, v66, v241
	v_mul_f32_e32 v67, v67, v241
	s_waitcnt lgkmcnt(0)
	s_barrier
; __device__ __forceinline__ void subln_store(f32x16 (&o)[4], const float* subg, bf16_t* dst  , int lane) {
;     const int hi = lane >> 5;
;     float ss = 0.f;
; #pragma unroll
;     for (int cb = 0; cb < 4; ++cb)
; #pragma unroll
;         for (int r = 0; r < 16; ++r) ss += o[cb][r] * o[cb][r];
;     ss += __shfl_xor(ss, 32);
;     const float rstd = (1.0f - LAMBDA_INIT) / sqrtf(ss * (1.0f / 128.0f) + EPS);
; __device__ __forceinline__ void attnA_unit(const P2Ctx& C, int b, int h, int qb) {
;     ...
;             for (int r = 0; r < 16; ++r) o[cb][r] = o[cb][r] * inv - lam * X2[((qs * 4 + cb) * 16 + r) * 64 + lane];
;         subln_store(o, C.a->in[I_SUBG], C.AO + qrow * DM + h * 128, lane);
	ds_read2st64_b32 v[164:165], v2 offset0:0 offset1:1
	ds_read2st64_b32 v[166:167], v2 offset0:2 offset1:3
	ds_read2st64_b32 v[168:169], v2 offset0:4 offset1:5
	ds_read2st64_b32 v[170:171], v2 offset0:6 offset1:7
	ds_read2st64_b32 v[172:173], v2 offset0:8 offset1:9
	ds_read2st64_b32 v[174:175], v2 offset0:10 offset1:11
	ds_read2st64_b32 v[176:177], v2 offset0:12 offset1:13
	ds_read2st64_b32 v[178:179], v2 offset0:14 offset1:15
	ds_read2st64_b32 v[180:181], v2 offset0:16 offset1:17
	ds_read2st64_b32 v[182:183], v2 offset0:18 offset1:19
	ds_read2st64_b32 v[184:185], v2 offset0:20 offset1:21
	ds_read2st64_b32 v[186:187], v2 offset0:22 offset1:23
	ds_read2st64_b32 v[188:189], v2 offset0:24 offset1:25
	ds_read2st64_b32 v[190:191], v2 offset0:26 offset1:27
	ds_read2st64_b32 v[192:193], v2 offset0:28 offset1:29
	s_waitcnt lgkmcnt(8)
	ds_read2st64_b32 v[194:195], v2 offset0:30 offset1:31
	ds_read2st64_b32 v[68:69], v2 offset0:32 offset1:33
	ds_read2st64_b32 v[70:71], v2 offset0:34 offset1:35
	ds_read2st64_b32 v[72:73], v2 offset0:36 offset1:37
	ds_read2st64_b32 v[74:75], v2 offset0:38 offset1:39
	ds_read2st64_b32 v[76:77], v2 offset0:40 offset1:41
	ds_read2st64_b32 v[78:79], v2 offset0:42 offset1:43
	ds_read2st64_b32 v[80:81], v2 offset0:44 offset1:45
	ds_read2st64_b32 v[82:83], v2 offset0:46 offset1:47
	ds_read2st64_b32 v[84:85], v2 offset0:48 offset1:49
	ds_read2st64_b32 v[86:87], v2 offset0:50 offset1:51
	ds_read2st64_b32 v[88:89], v2 offset0:52 offset1:53
	ds_read2st64_b32 v[90:91], v2 offset0:54 offset1:55
	ds_read2st64_b32 v[92:93], v2 offset0:56 offset1:57
	ds_read2st64_b32 v[94:95], v2 offset0:58 offset1:59
	ds_read2st64_b32 v[96:97], v2 offset0:60 offset1:61
	ds_read2st64_b32 v[98:99], v2 offset0:62 offset1:63
	s_waitcnt lgkmcnt(0)
	v_fma_f32 v4, -v243, v164, v4
	v_fma_f32 v5, -v243, v165, v5
	v_fma_f32 v6, -v243, v166, v6
	v_fma_f32 v7, -v243, v167, v7
	v_fma_f32 v8, -v243, v168, v8
	v_fma_f32 v9, -v243, v169, v9
	v_fma_f32 v10, -v243, v170, v10
	v_fma_f32 v11, -v243, v171, v11
	v_fma_f32 v12, -v243, v172, v12
	v_fma_f32 v13, -v243, v173, v13
	v_fma_f32 v14, -v243, v174, v14
	v_fma_f32 v15, -v243, v175, v15
	v_fma_f32 v16, -v243, v176, v16
	v_fma_f32 v17, -v243, v177, v17
	v_fma_f32 v18, -v243, v178, v18
	v_fma_f32 v19, -v243, v179, v19
	v_fma_f32 v20, -v243, v180, v20
	v_fma_f32 v21, -v243, v181, v21
	v_fma_f32 v22, -v243, v182, v22
	v_fma_f32 v23, -v243, v183, v23
	v_fma_f32 v24, -v243, v184, v24
	v_fma_f32 v25, -v243, v185, v25
	v_fma_f32 v26, -v243, v186, v26
	v_fma_f32 v27, -v243, v187, v27
	v_fma_f32 v28, -v243, v188, v28
	v_fma_f32 v29, -v243, v189, v29
	v_fma_f32 v30, -v243, v190, v30
	v_fma_f32 v31, -v243, v191, v31
	v_fma_f32 v32, -v243, v192, v32
	v_fma_f32 v33, -v243, v193, v33
	v_fma_f32 v34, -v243, v194, v34
	v_fma_f32 v35, -v243, v195, v35
	v_fma_f32 v36, -v243, v68, v36
	v_fma_f32 v37, -v243, v69, v37
	v_fma_f32 v38, -v243, v70, v38
	v_fma_f32 v39, -v243, v71, v39
	v_fma_f32 v40, -v243, v72, v40
	v_fma_f32 v41, -v243, v73, v41
	v_fma_f32 v42, -v243, v74, v42
	v_fma_f32 v43, -v243, v75, v43
	v_fma_f32 v44, -v243, v76, v44
	v_fma_f32 v45, -v243, v77, v45
	v_fma_f32 v46, -v243, v78, v46
	v_fma_f32 v47, -v243, v79, v47
	v_fma_f32 v48, -v243, v80, v48
	v_fma_f32 v49, -v243, v81, v49
	v_fma_f32 v50, -v243, v82, v50
	v_fma_f32 v51, -v243, v83, v51
	v_fma_f32 v52, -v243, v84, v52
	v_fma_f32 v53, -v243, v85, v53
	v_fma_f32 v54, -v243, v86, v54
	v_fma_f32 v55, -v243, v87, v55
	v_fma_f32 v56, -v243, v88, v56
	v_fma_f32 v57, -v243, v89, v57
	v_fma_f32 v58, -v243, v90, v58
	v_fma_f32 v59, -v243, v91, v59
	v_fma_f32 v60, -v243, v92, v60
	v_fma_f32 v61, -v243, v93, v61
	v_fma_f32 v62, -v243, v94, v62
	v_fma_f32 v63, -v243, v95, v63
	v_fma_f32 v64, -v243, v96, v64
	v_fma_f32 v65, -v243, v97, v65
	v_fma_f32 v66, -v243, v98, v66
	v_fma_f32 v67, -v243, v99, v67
	v_mul_f32_e32 v245, v4, v4
	v_fmac_f32_e32 v245, v5, v5
	v_fmac_f32_e32 v245, v6, v6
	v_fmac_f32_e32 v245, v7, v7
	v_fmac_f32_e32 v245, v8, v8
	v_fmac_f32_e32 v245, v9, v9
	v_fmac_f32_e32 v245, v10, v10
	v_fmac_f32_e32 v245, v11, v11
	v_fmac_f32_e32 v245, v12, v12
	v_fmac_f32_e32 v245, v13, v13
	v_fmac_f32_e32 v245, v14, v14
	v_fmac_f32_e32 v245, v15, v15
	v_fmac_f32_e32 v245, v16, v16
	v_fmac_f32_e32 v245, v17, v17
	v_fmac_f32_e32 v245, v18, v18
	v_fmac_f32_e32 v245, v19, v19
	v_fmac_f32_e32 v245, v20, v20
	v_fmac_f32_e32 v245, v21, v21
	v_fmac_f32_e32 v245, v22, v22
	v_fmac_f32_e32 v245, v23, v23
	v_fmac_f32_e32 v245, v24, v24
	v_fmac_f32_e32 v245, v25, v25
	v_fmac_f32_e32 v245, v26, v26
	v_fmac_f32_e32 v245, v27, v27
	v_fmac_f32_e32 v245, v28, v28
	v_fmac_f32_e32 v245, v29, v29
	v_fmac_f32_e32 v245, v30, v30
	v_fmac_f32_e32 v245, v31, v31
	v_fmac_f32_e32 v245, v32, v32
	v_fmac_f32_e32 v245, v33, v33
	v_fmac_f32_e32 v245, v34, v34
	v_fmac_f32_e32 v245, v35, v35
	v_fmac_f32_e32 v245, v36, v36
	v_fmac_f32_e32 v245, v37, v37
	v_fmac_f32_e32 v245, v38, v38
	v_fmac_f32_e32 v245, v39, v39
	v_fmac_f32_e32 v245, v40, v40
	v_fmac_f32_e32 v245, v41, v41
	v_fmac_f32_e32 v245, v42, v42
	v_fmac_f32_e32 v245, v43, v43
	v_fmac_f32_e32 v245, v44, v44
	v_fmac_f32_e32 v245, v45, v45
	v_fmac_f32_e32 v245, v46, v46
	v_fmac_f32_e32 v245, v47, v47
	v_fmac_f32_e32 v245, v48, v48
	v_fmac_f32_e32 v245, v49, v49
	v_fmac_f32_e32 v245, v50, v50
	v_fmac_f32_e32 v245, v51, v51
	v_fmac_f32_e32 v245, v52, v52
	v_fmac_f32_e32 v245, v53, v53
	v_fmac_f32_e32 v245, v54, v54
	v_fmac_f32_e32 v245, v55, v55
	v_fmac_f32_e32 v245, v56, v56
	v_fmac_f32_e32 v245, v57, v57
	v_fmac_f32_e32 v245, v58, v58
	v_fmac_f32_e32 v245, v59, v59
	v_fmac_f32_e32 v245, v60, v60
	v_fmac_f32_e32 v245, v61, v61
	v_fmac_f32_e32 v245, v62, v62
	v_fmac_f32_e32 v245, v63, v63
	v_fmac_f32_e32 v245, v64, v64
	v_fmac_f32_e32 v245, v65, v65
	v_fmac_f32_e32 v245, v66, v66
	v_fmac_f32_e32 v245, v67, v67
	v_mov_b32_e32 v246, v245
	s_nop 1
	v_permlane32_swap_b32 v246, v245
	v_add_f32_e32 v245, v246, v245
	v_mov_b32_e32 v246, 0x3c000000
	v_fmaak_f32 v245, v245, v246, 0x358637bd
	v_rsq_f32_e32 v245, v245
	s_nop 0
	v_mul_f32_e32 v245, 0x3f4ccccd, v245
	s_lshl_b32 s6, s11, 11
	s_add_i32 s6, s6, s15
	s_lshl_b32 s6, s6, 11
	s_lshl_b32 s7, s81, 1
	s_add_i32 s6, s6, s7
	s_add_u32 s20, s70, s6
	s_addc_u32 s21, s71, 0
	v_and_b32_e32 v242, 31, v219
	v_lshlrev_b32_e32 v242, 11, v242
	v_lshrrev_b32_e32 v243, 5, v219
	v_lshl_add_u32 v242, v243, 4, v242
	s_waitcnt vmcnt(0)
; __device__ __forceinline__ unsigned pk_bf16(float lo, float hi) { f32x2 v = {lo, hi}; bf16x2_t b = __builtin_convertvector(v, bf16x2_t); return __builtin_bit_cast(unsigned, b); }
; __device__ __forceinline__ void subln_store(f32x16 (&o)[4], const float* subg, bf16_t* dst  , int lane) {
;     ...
;     for (int cb = 0; cb < 4; ++cb)
; #pragma unroll
;         for (int g = 0; g < 4; ++g) { const int dv0 = 32 * cb + 8 * g + 4 * hi; const f32x4 s4 = sg[cb][g];
;             u32x2 w; w.x = pk_bf16(o[cb][4 * g + 0] * rstd * s4[0], o[cb][4 * g + 1] * rstd * s4[1]); w.y = pk_bf16(o[cb][4 * g + 2] * rstd * s4[2], o[cb][4 * g + 3] * rstd * s4[3]);
;             *(u32x2*)(dst + dv0) = w; }
	v_mul_f32_e32 v4, v4, v245
	v_mul_f32_e32 v5, v5, v245
	v_mul_f32_e32 v6, v6, v245
	v_mul_f32_e32 v7, v7, v245
	v_mul_f32_e32 v4, v4, v100
	v_mul_f32_e32 v5, v5, v101
	v_mul_f32_e32 v6, v6, v102
	v_mul_f32_e32 v7, v7, v103
	v_mul_f32_e32 v8, v8, v245
	v_mul_f32_e32 v9, v9, v245
	v_mul_f32_e32 v10, v10, v245
	v_mul_f32_e32 v11, v11, v245
	v_mul_f32_e32 v8, v8, v104
	v_mul_f32_e32 v9, v9, v105
	v_mul_f32_e32 v10, v10, v106
	v_mul_f32_e32 v11, v11, v107
	v_cvt_pk_bf16_f32 v68, v4, v5
	v_cvt_pk_bf16_f32 v69, v6, v7
	v_cvt_pk_bf16_f32 v70, v8, v9
	v_cvt_pk_bf16_f32 v71, v10, v11
	s_nop 1
	v_permlane32_swap_b32 v68, v70
	v_permlane32_swap_b32 v69, v71
	global_store_dwordx4 v242, v[68:71], s[20:21] offset:0
	v_mul_f32_e32 v12, v12, v245
	v_mul_f32_e32 v13, v13, v245
	v_mul_f32_e32 v14, v14, v245
	v_mul_f32_e32 v15, v15, v245
	v_mul_f32_e32 v12, v12, v108
	v_mul_f32_e32 v13, v13, v109
	v_mul_f32_e32 v14, v14, v110
	v_mul_f32_e32 v15, v15, v111
	v_mul_f32_e32 v16, v16, v245
	v_mul_f32_e32 v17, v17, v245
	v_mul_f32_e32 v18, v18, v245
	v_mul_f32_e32 v19, v19, v245
	v_mul_f32_e32 v16, v16, v112
	v_mul_f32_e32 v17, v17, v113
	v_mul_f32_e32 v18, v18, v114
	v_mul_f32_e32 v19, v19, v115
	v_cvt_pk_bf16_f32 v72, v12, v13
	v_cvt_pk_bf16_f32 v73, v14, v15
	v_cvt_pk_bf16_f32 v74, v16, v17
	v_cvt_pk_bf16_f32 v75, v18, v19
	s_nop 1
	v_permlane32_swap_b32 v72, v74
	v_permlane32_swap_b32 v73, v75
	global_store_dwordx4 v242, v[72:75], s[20:21] offset:32
	v_mul_f32_e32 v20, v20, v245
	v_mul_f32_e32 v21, v21, v245
	v_mul_f32_e32 v22, v22, v245
	v_mul_f32_e32 v23, v23, v245
	v_mul_f32_e32 v20, v20, v116
	v_mul_f32_e32 v21, v21, v117
	v_mul_f32_e32 v22, v22, v118
	v_mul_f32_e32 v23, v23, v119
	v_mul_f32_e32 v24, v24, v245
	v_mul_f32_e32 v25, v25, v245
	v_mul_f32_e32 v26, v26, v245
	v_mul_f32_e32 v27, v27, v245
	v_mul_f32_e32 v24, v24, v120
	v_mul_f32_e32 v25, v25, v121
	v_mul_f32_e32 v26, v26, v122
	v_mul_f32_e32 v27, v27, v123
	v_cvt_pk_bf16_f32 v68, v20, v21
	v_cvt_pk_bf16_f32 v69, v22, v23
	v_cvt_pk_bf16_f32 v70, v24, v25
	v_cvt_pk_bf16_f32 v71, v26, v27
	s_nop 1
	v_permlane32_swap_b32 v68, v70
	v_permlane32_swap_b32 v69, v71
	global_store_dwordx4 v242, v[68:71], s[20:21] offset:64
	v_mul_f32_e32 v28, v28, v245
	v_mul_f32_e32 v29, v29, v245
	v_mul_f32_e32 v30, v30, v245
	v_mul_f32_e32 v31, v31, v245
	v_mul_f32_e32 v28, v28, v124
	v_mul_f32_e32 v29, v29, v125
	v_mul_f32_e32 v30, v30, v126
	v_mul_f32_e32 v31, v31, v127
	v_mul_f32_e32 v32, v32, v245
	v_mul_f32_e32 v33, v33, v245
	v_mul_f32_e32 v34, v34, v245
	v_mul_f32_e32 v35, v35, v245
	v_mul_f32_e32 v32, v32, v128
	v_mul_f32_e32 v33, v33, v129
	v_mul_f32_e32 v34, v34, v130
	v_mul_f32_e32 v35, v35, v131
	v_cvt_pk_bf16_f32 v72, v28, v29
	v_cvt_pk_bf16_f32 v73, v30, v31
	v_cvt_pk_bf16_f32 v74, v32, v33
	v_cvt_pk_bf16_f32 v75, v34, v35
	s_nop 1
	v_permlane32_swap_b32 v72, v74
	v_permlane32_swap_b32 v73, v75
	global_store_dwordx4 v242, v[72:75], s[20:21] offset:96
	v_mul_f32_e32 v36, v36, v245
	v_mul_f32_e32 v37, v37, v245
	v_mul_f32_e32 v38, v38, v245
	v_mul_f32_e32 v39, v39, v245
	v_mul_f32_e32 v36, v36, v132
	v_mul_f32_e32 v37, v37, v133
	v_mul_f32_e32 v38, v38, v134
	v_mul_f32_e32 v39, v39, v135
	v_mul_f32_e32 v40, v40, v245
	v_mul_f32_e32 v41, v41, v245
	v_mul_f32_e32 v42, v42, v245
	v_mul_f32_e32 v43, v43, v245
	v_mul_f32_e32 v40, v40, v136
	v_mul_f32_e32 v41, v41, v137
	v_mul_f32_e32 v42, v42, v138
	v_mul_f32_e32 v43, v43, v139
	v_cvt_pk_bf16_f32 v68, v36, v37
	v_cvt_pk_bf16_f32 v69, v38, v39
	v_cvt_pk_bf16_f32 v70, v40, v41
	v_cvt_pk_bf16_f32 v71, v42, v43
	s_nop 1
	v_permlane32_swap_b32 v68, v70
	v_permlane32_swap_b32 v69, v71
	global_store_dwordx4 v242, v[68:71], s[20:21] offset:128
	v_mul_f32_e32 v44, v44, v245
	v_mul_f32_e32 v45, v45, v245
	v_mul_f32_e32 v46, v46, v245
	v_mul_f32_e32 v47, v47, v245
	v_mul_f32_e32 v44, v44, v140
	v_mul_f32_e32 v45, v45, v141
	v_mul_f32_e32 v46, v46, v142
	v_mul_f32_e32 v47, v47, v143
	v_mul_f32_e32 v48, v48, v245
	v_mul_f32_e32 v49, v49, v245
	v_mul_f32_e32 v50, v50, v245
	v_mul_f32_e32 v51, v51, v245
	v_mul_f32_e32 v48, v48, v144
	v_mul_f32_e32 v49, v49, v145
	v_mul_f32_e32 v50, v50, v146
	v_mul_f32_e32 v51, v51, v147
	v_cvt_pk_bf16_f32 v72, v44, v45
	v_cvt_pk_bf16_f32 v73, v46, v47
	v_cvt_pk_bf16_f32 v74, v48, v49
	v_cvt_pk_bf16_f32 v75, v50, v51
	s_nop 1
	v_permlane32_swap_b32 v72, v74
	v_permlane32_swap_b32 v73, v75
	global_store_dwordx4 v242, v[72:75], s[20:21] offset:160
	v_mul_f32_e32 v52, v52, v245
	v_mul_f32_e32 v53, v53, v245
	v_mul_f32_e32 v54, v54, v245
	v_mul_f32_e32 v55, v55, v245
	v_mul_f32_e32 v52, v52, v148
	v_mul_f32_e32 v53, v53, v149
	v_mul_f32_e32 v54, v54, v150
	v_mul_f32_e32 v55, v55, v151
	v_mul_f32_e32 v56, v56, v245
	v_mul_f32_e32 v57, v57, v245
	v_mul_f32_e32 v58, v58, v245
	v_mul_f32_e32 v59, v59, v245
	v_mul_f32_e32 v56, v56, v152
	v_mul_f32_e32 v57, v57, v153
	v_mul_f32_e32 v58, v58, v154
	v_mul_f32_e32 v59, v59, v155
	v_cvt_pk_bf16_f32 v68, v52, v53
	v_cvt_pk_bf16_f32 v69, v54, v55
	v_cvt_pk_bf16_f32 v70, v56, v57
	v_cvt_pk_bf16_f32 v71, v58, v59
	s_nop 1
	v_permlane32_swap_b32 v68, v70
	v_permlane32_swap_b32 v69, v71
	global_store_dwordx4 v242, v[68:71], s[20:21] offset:192
	v_mul_f32_e32 v60, v60, v245
	v_mul_f32_e32 v61, v61, v245
	v_mul_f32_e32 v62, v62, v245
	v_mul_f32_e32 v63, v63, v245
	v_mul_f32_e32 v60, v60, v156
	v_mul_f32_e32 v61, v61, v157
	v_mul_f32_e32 v62, v62, v158
	v_mul_f32_e32 v63, v63, v159
	v_mul_f32_e32 v64, v64, v245
	v_mul_f32_e32 v65, v65, v245
	v_mul_f32_e32 v66, v66, v245
	v_mul_f32_e32 v67, v67, v245
	v_mul_f32_e32 v64, v64, v160
	v_mul_f32_e32 v65, v65, v161
	v_mul_f32_e32 v66, v66, v162
	v_mul_f32_e32 v67, v67, v163
	v_cvt_pk_bf16_f32 v72, v60, v61
	v_cvt_pk_bf16_f32 v73, v62, v63
	v_cvt_pk_bf16_f32 v74, v64, v65
	v_cvt_pk_bf16_f32 v75, v66, v67
	s_nop 1
	v_permlane32_swap_b32 v72, v74
	v_permlane32_swap_b32 v73, v75
	global_store_dwordx4 v242, v[72:75], s[20:21] offset:224
